# decode attention (the loop copy that runs with a full grid): storing path waits once for the batch loads, no per-store vmcnt ladder
# speedup vs baseline: 1.0044x; 1.0005x over previous
.LBB0_450:
	v_min_i32_e32 v0, v141, v207
	v_sub_u32_e32 v0, 0x80, v0
	v_add_u32_e32 v222, 1, v141
	v_lshl_add_u32 v56, v0, v210, v143
	v_min_i32_e32 v0, v222, v207
	v_sub_u32_e32 v0, 0x80, v0
	v_add_u32_e32 v221, 2, v141
	v_lshl_add_u32 v58, v0, v210, v143
	v_min_i32_e32 v0, v221, v207
	v_sub_u32_e32 v0, 0x80, v0
	v_add_u32_e32 v216, 3, v141
	v_lshl_add_u32 v60, v0, v210, v143
	v_min_i32_e32 v0, v216, v207
	v_sub_u32_e32 v0, 0x80, v0
	v_add_u32_e32 v215, 4, v141
	v_lshl_add_u32 v62, v0, v210, v143
	v_min_i32_e32 v0, v215, v207
	v_sub_u32_e32 v0, 0x80, v0
	v_add_u32_e32 v214, 5, v141
	v_lshl_add_u32 v64, v0, v210, v143
	v_min_i32_e32 v0, v214, v207
	v_ashrrev_i32_e32 v57, 31, v56
	v_sub_u32_e32 v0, 0x80, v0
	v_add_u32_e32 v213, 6, v141
	v_lshlrev_b64 v[56:57], 11, v[56:57]
	v_ashrrev_i32_e32 v59, 31, v58
	v_ashrrev_i32_e32 v61, 31, v60
	v_ashrrev_i32_e32 v63, 31, v62
	v_lshl_add_u32 v66, v0, v210, v143
	v_min_i32_e32 v0, v213, v207
	v_lshl_add_u64 v[56:57], v[2:3], 0, v[56:57]
	v_lshlrev_b64 v[58:59], 11, v[58:59]
	v_lshlrev_b64 v[60:61], 11, v[60:61]
	v_lshlrev_b64 v[62:63], 11, v[62:63]
	v_sub_u32_e32 v0, 0x80, v0
	global_load_dwordx4 v[116:119], v[56:57], off
	v_lshl_add_u64 v[58:59], v[2:3], 0, v[58:59]
	v_lshl_add_u64 v[60:61], v[2:3], 0, v[60:61]
	v_lshl_add_u64 v[62:63], v[2:3], 0, v[62:63]
	v_lshl_add_u32 v68, v0, v210, v143
	global_load_dwordx4 v[112:115], v[58:59], off
	global_load_dwordx4 v[108:111], v[60:61], off
	global_load_dwordx4 v[104:107], v[62:63], off
	v_ashrrev_i32_e32 v65, 31, v64
	v_ashrrev_i32_e32 v67, 31, v66
	v_ashrrev_i32_e32 v69, 31, v68
	v_lshlrev_b64 v[64:65], 11, v[64:65]
	v_lshlrev_b64 v[66:67], 11, v[66:67]
	v_lshlrev_b64 v[68:69], 11, v[68:69]
	v_lshl_add_u64 v[64:65], v[2:3], 0, v[64:65]
	v_lshl_add_u64 v[66:67], v[2:3], 0, v[66:67]
	v_lshl_add_u64 v[156:157], v[2:3], 0, v[68:69]
	global_load_dwordx4 v[100:103], v[64:65], off
	global_load_dwordx4 v[96:99], v[66:67], off
	global_load_dwordx4 v[92:95], v[156:157], off
	v_add_u32_e32 v212, 7, v141
	v_min_i32_e32 v0, v212, v207
	v_sub_u32_e32 v0, 0x80, v0
	v_lshl_add_u32 v68, v0, v210, v143
	v_ashrrev_i32_e32 v69, 31, v68
	v_lshlrev_b64 v[68:69], 11, v[68:69]
	v_lshl_add_u64 v[158:159], v[2:3], 0, v[68:69]
	global_load_dwordx4 v[88:91], v[158:159], off
	global_load_dwordx4 v[84:87], v[56:57], off offset:1024
	global_load_dwordx4 v[80:83], v[58:59], off offset:1024
	global_load_dwordx4 v[76:79], v[60:61], off offset:1024
	global_load_dwordx4 v[72:75], v[62:63], off offset:1024
	global_load_dwordx4 v[68:71], v[64:65], off offset:1024
	s_nop 0
	global_load_dwordx4 v[64:67], v[66:67], off offset:1024
	s_nop 0
	global_load_dwordx4 v[60:63], v[156:157], off offset:1024
	global_load_dwordx4 v[56:59], v[158:159], off offset:1024
	s_waitcnt vmcnt(15)
	v_pk_mul_f32 v[156:157], v[116:117], v[150:151]
	v_pk_mul_f32 v[158:159], v[118:119], v[152:153]
	v_add_f32_e32 v0, v156, v157
	v_add_f32_e32 v0, v158, v0
	v_add_f32_e32 v0, v159, v0
	s_waitcnt vmcnt(14)
	v_pk_mul_f32 v[156:157], v[112:113], v[150:151]
	s_waitcnt vmcnt(13)
	v_pk_mul_f32 v[162:163], v[108:109], v[150:151]
	s_waitcnt vmcnt(12)
	v_pk_mul_f32 v[166:167], v[104:105], v[150:151]
	v_pk_mul_f32 v[160:161], v[114:115], v[152:153]
	v_pk_mul_f32 v[164:165], v[110:111], v[152:153]
	v_pk_mul_f32 v[188:189], v[106:107], v[152:153]
	v_add_f32_e32 v148, v156, v157
	v_mov_b32_e32 v156, v166
	v_mov_b32_e32 v157, v162
	v_mov_b32_e32 v162, v167
	v_add_f32_e32 v148, v160, v148
	v_pk_add_f32 v[156:157], v[156:157], v[162:163]
	v_mov_b32_e32 v158, v188
	v_mov_b32_e32 v159, v164
	s_waitcnt vmcnt(11)
	v_pk_mul_f32 v[224:225], v[100:101], v[150:151]
	v_add_f32_e32 v148, v161, v148
	s_waitcnt vmcnt(10)
	v_pk_mul_f32 v[160:161], v[96:97], v[150:151]
	s_waitcnt vmcnt(9)
	v_pk_mul_f32 v[230:231], v[92:93], v[150:151]
	s_waitcnt vmcnt(8)
	v_pk_mul_f32 v[234:235], v[88:89], v[150:151]
	v_pk_add_f32 v[156:157], v[158:159], v[156:157]
	v_mov_b32_e32 v164, v189
	v_pk_mul_f32 v[226:227], v[102:103], v[152:153]
	v_pk_mul_f32 v[228:229], v[98:99], v[152:153]
	v_pk_mul_f32 v[232:233], v[94:95], v[152:153]
	v_pk_mul_f32 v[236:237], v[90:91], v[152:153]
	v_pk_add_f32 v[156:157], v[164:165], v[156:157]
	v_mov_b32_e32 v162, v160
	v_mov_b32_e32 v163, v224
	v_mov_b32_e32 v224, v161
	v_mov_b32_e32 v164, v234
	v_mov_b32_e32 v165, v230
	v_mov_b32_e32 v230, v235
	v_pk_add_f32 v[160:161], v[162:163], v[224:225]
	v_mov_b32_e32 v162, v228
	v_mov_b32_e32 v163, v226
	v_pk_add_f32 v[164:165], v[164:165], v[230:231]
	v_mov_b32_e32 v166, v236
	v_mov_b32_e32 v167, v232
	v_pk_add_f32 v[160:161], v[162:163], v[160:161]
	v_mov_b32_e32 v226, v229
	v_pk_add_f32 v[164:165], v[166:167], v[164:165]
	v_mov_b32_e32 v232, v237
	v_pk_add_f32 v[160:161], v[226:227], v[160:161]
	v_pk_add_f32 v[164:165], v[232:233], v[164:165]
	v_mov_b32_dpp v159, v157 quad_perm:[1,0,3,2] row_mask:0xf bank_mask:0xf bound_ctrl:1
	v_mov_b32_dpp v158, v156 quad_perm:[1,0,3,2] row_mask:0xf bank_mask:0xf bound_ctrl:1
	v_mov_b32_dpp v163, v161 quad_perm:[1,0,3,2] row_mask:0xf bank_mask:0xf bound_ctrl:1
	v_mov_b32_dpp v162, v160 quad_perm:[1,0,3,2] row_mask:0xf bank_mask:0xf bound_ctrl:1
	v_mov_b32_dpp v167, v165 quad_perm:[1,0,3,2] row_mask:0xf bank_mask:0xf bound_ctrl:1
	v_mov_b32_dpp v166, v164 quad_perm:[1,0,3,2] row_mask:0xf bank_mask:0xf bound_ctrl:1
	v_pk_add_f32 v[156:157], v[156:157], v[158:159]
	v_pk_add_f32 v[160:161], v[160:161], v[162:163]
	v_pk_add_f32 v[164:165], v[164:165], v[166:167]
	v_add_f32_dpp v0, v0, v0 quad_perm:[1,0,3,2] row_mask:0xf bank_mask:0xf bound_ctrl:1
	v_mov_b32_dpp v159, v157 quad_perm:[2,3,0,1] row_mask:0xf bank_mask:0xf bound_ctrl:1
	v_mov_b32_dpp v158, v156 quad_perm:[2,3,0,1] row_mask:0xf bank_mask:0xf bound_ctrl:1
	v_mov_b32_dpp v163, v161 quad_perm:[2,3,0,1] row_mask:0xf bank_mask:0xf bound_ctrl:1
	v_mov_b32_dpp v162, v160 quad_perm:[2,3,0,1] row_mask:0xf bank_mask:0xf bound_ctrl:1
	v_mov_b32_dpp v167, v165 quad_perm:[2,3,0,1] row_mask:0xf bank_mask:0xf bound_ctrl:1
	v_mov_b32_dpp v166, v164 quad_perm:[2,3,0,1] row_mask:0xf bank_mask:0xf bound_ctrl:1
	v_add_f32_dpp v0, v0, v0 quad_perm:[2,3,0,1] row_mask:0xf bank_mask:0xf bound_ctrl:1
	v_add_f32_dpp v148, v148, v148 quad_perm:[1,0,3,2] row_mask:0xf bank_mask:0xf bound_ctrl:1
	v_pk_add_f32 v[156:157], v[156:157], v[158:159]
	v_pk_add_f32 v[160:161], v[160:161], v[162:163]
	v_pk_add_f32 v[164:165], v[164:165], v[166:167]
	v_add_f32_dpp v217, v0, v0 row_half_mirror row_mask:0xf bank_mask:0xf bound_ctrl:1
	v_add_f32_dpp v0, v148, v148 quad_perm:[2,3,0,1] row_mask:0xf bank_mask:0xf bound_ctrl:1
	v_mov_b32_dpp v159, v157 row_half_mirror row_mask:0xf bank_mask:0xf bound_ctrl:1
	v_mov_b32_dpp v158, v156 row_half_mirror row_mask:0xf bank_mask:0xf bound_ctrl:1
	v_mov_b32_dpp v163, v161 row_half_mirror row_mask:0xf bank_mask:0xf bound_ctrl:1
	v_mov_b32_dpp v162, v160 row_half_mirror row_mask:0xf bank_mask:0xf bound_ctrl:1
	v_mov_b32_dpp v167, v165 row_half_mirror row_mask:0xf bank_mask:0xf bound_ctrl:1
	v_mov_b32_dpp v166, v164 row_half_mirror row_mask:0xf bank_mask:0xf bound_ctrl:1
	v_add_f32_dpp v219, v0, v0 row_half_mirror row_mask:0xf bank_mask:0xf bound_ctrl:1
	v_pk_add_f32 v[156:157], v[156:157], v[158:159]
	v_pk_add_f32 v[160:161], v[160:161], v[162:163]
	v_pk_add_f32 v[164:165], v[164:165], v[166:167]
	v_mov_b32_dpp v218, v217 row_mirror row_mask:0xf bank_mask:0xf bound_ctrl:1
	v_mov_b32_dpp v220, v219 row_mirror row_mask:0xf bank_mask:0xf bound_ctrl:1
	v_mov_b32_dpp v159, v157 row_mirror row_mask:0xf bank_mask:0xf bound_ctrl:1
	v_mov_b32_dpp v158, v156 row_mirror row_mask:0xf bank_mask:0xf bound_ctrl:1
	v_mov_b32_dpp v163, v161 row_mirror row_mask:0xf bank_mask:0xf bound_ctrl:1
	v_mov_b32_dpp v162, v160 row_mirror row_mask:0xf bank_mask:0xf bound_ctrl:1
	v_mov_b32_dpp v167, v165 row_mirror row_mask:0xf bank_mask:0xf bound_ctrl:1
	v_mov_b32_dpp v166, v164 row_mirror row_mask:0xf bank_mask:0xf bound_ctrl:1
	s_and_saveexec_b64 s[28:29], s[60:61]
	s_cbranch_execz .LBB0_449
	s_waitcnt vmcnt(0)
	v_add_u32_e32 v0, 7, v211
	v_lshl_add_u32 v0, v0, v210, v143
	v_cmp_lt_i32_e32 vcc, 7, v0
	s_and_saveexec_b64 s[30:31], vcc
	s_cbranch_execz .LBB0_453
	v_add_u32_e32 v0, -8, v0
	v_lshlrev_b64 v[188:189], 11, v[0:1]
	v_lshl_add_u64 v[188:189], v[154:155], 0, v[188:189]
	global_store_dwordx4 v[188:189], v[116:119], off nt
	s_nop 0
	global_store_dwordx4 v[188:189], v[84:87], off offset:1024 nt
.LBB0_453:
	s_or_b64 exec, exec, s[30:31]
	v_add_u32_e32 v0, 6, v211
	v_lshl_add_u32 v0, v0, v210, v143
	v_cmp_lt_u32_e32 vcc, v222, v206
	v_cmp_lt_i32_e64 s[48:49], 7, v0
	s_and_b64 s[14:15], vcc, s[48:49]
	s_and_saveexec_b64 s[30:31], s[14:15]
	s_cbranch_execz .LBB0_455
	v_add_u32_e32 v0, -8, v0
	v_lshlrev_b64 v[116:117], 11, v[0:1]
	v_lshl_add_u64 v[116:117], v[154:155], 0, v[116:117]
	global_store_dwordx4 v[116:117], v[112:115], off nt
	s_nop 0
	global_store_dwordx4 v[116:117], v[80:83], off offset:1024 nt
.LBB0_455:
	s_or_b64 exec, exec, s[30:31]
	v_add_u32_e32 v0, 5, v211
	v_lshl_add_u32 v0, v0, v210, v143
	v_cmp_lt_u32_e32 vcc, v221, v206
	v_cmp_lt_i32_e64 s[48:49], 7, v0
	s_and_b64 s[14:15], vcc, s[48:49]
	s_and_saveexec_b64 s[30:31], s[14:15]
	s_cbranch_execz .LBB0_457
	v_add_u32_e32 v0, -8, v0
	v_lshlrev_b64 v[112:113], 11, v[0:1]
	v_lshl_add_u64 v[112:113], v[154:155], 0, v[112:113]
	global_store_dwordx4 v[112:113], v[108:111], off nt
	s_nop 0
	global_store_dwordx4 v[112:113], v[76:79], off offset:1024 nt
.LBB0_457:
	s_or_b64 exec, exec, s[30:31]
	v_add_u32_e32 v0, 4, v211
	v_lshl_add_u32 v0, v0, v210, v143
	v_cmp_lt_u32_e32 vcc, v216, v206
	v_cmp_lt_i32_e64 s[48:49], 7, v0
	s_and_b64 s[14:15], vcc, s[48:49]
	s_and_saveexec_b64 s[30:31], s[14:15]
	s_cbranch_execz .LBB0_459
	v_add_u32_e32 v0, -8, v0
	v_lshlrev_b64 v[108:109], 11, v[0:1]
	v_lshl_add_u64 v[108:109], v[154:155], 0, v[108:109]
	global_store_dwordx4 v[108:109], v[104:107], off nt
	s_nop 0
	global_store_dwordx4 v[108:109], v[72:75], off offset:1024 nt
.LBB0_459:
	s_or_b64 exec, exec, s[30:31]
	v_add_u32_e32 v0, 3, v211
	v_lshl_add_u32 v0, v0, v210, v143
	v_cmp_lt_u32_e32 vcc, v215, v206
	v_cmp_lt_i32_e64 s[48:49], 7, v0
	s_and_b64 s[14:15], vcc, s[48:49]
	s_and_saveexec_b64 s[30:31], s[14:15]
	s_cbranch_execz .LBB0_461
	v_add_u32_e32 v0, -8, v0
	v_lshlrev_b64 v[104:105], 11, v[0:1]
	v_lshl_add_u64 v[104:105], v[154:155], 0, v[104:105]
	global_store_dwordx4 v[104:105], v[100:103], off nt
	s_nop 0
	global_store_dwordx4 v[104:105], v[68:71], off offset:1024 nt
.LBB0_461:
	s_or_b64 exec, exec, s[30:31]
	v_add_u32_e32 v0, 2, v211
	v_lshl_add_u32 v0, v0, v210, v143
	v_cmp_lt_u32_e32 vcc, v214, v206
	v_cmp_lt_i32_e64 s[48:49], 7, v0
	s_and_b64 s[14:15], vcc, s[48:49]
	s_and_saveexec_b64 s[30:31], s[14:15]
	s_cbranch_execz .LBB0_463
	v_add_u32_e32 v0, -8, v0
	v_lshlrev_b64 v[100:101], 11, v[0:1]
	v_lshl_add_u64 v[100:101], v[154:155], 0, v[100:101]
	global_store_dwordx4 v[100:101], v[96:99], off nt
	s_nop 0
	global_store_dwordx4 v[100:101], v[64:67], off offset:1024 nt
.LBB0_463:
	s_or_b64 exec, exec, s[30:31]
	v_add_u32_e32 v0, 1, v211
	v_lshl_add_u32 v0, v0, v210, v143
	v_cmp_lt_u32_e32 vcc, v213, v206
	v_cmp_lt_i32_e64 s[48:49], 7, v0
	s_and_b64 s[14:15], vcc, s[48:49]
	s_and_saveexec_b64 s[30:31], s[14:15]
	s_cbranch_execz .LBB0_465
	v_add_u32_e32 v0, -8, v0
	v_lshlrev_b64 v[96:97], 11, v[0:1]
	v_lshl_add_u64 v[96:97], v[154:155], 0, v[96:97]
	global_store_dwordx4 v[96:97], v[92:95], off nt
	s_nop 0
	global_store_dwordx4 v[96:97], v[60:63], off offset:1024 nt
.LBB0_465:
	s_or_b64 exec, exec, s[30:31]
	v_lshl_add_u32 v0, v211, v210, v143
	v_cmp_lt_u32_e32 vcc, v212, v206
	v_cmp_lt_i32_e64 s[48:49], 7, v0
	s_and_b64 s[14:15], vcc, s[48:49]
	s_and_b64 exec, exec, s[14:15]
	s_cbranch_execz .Lsm_nw2
	v_add_u32_e32 v0, -8, v0
	v_lshlrev_b64 v[92:93], 11, v[0:1]
	v_lshl_add_u64 v[92:93], v[154:155], 0, v[92:93]
	global_store_dwordx4 v[92:93], v[88:91], off nt
	s_nop 0
	global_store_dwordx4 v[92:93], v[56:59], off offset:1024 nt
.Lsm_nw2:
	s_or_b64 exec, exec, s[28:29]
	v_add3_u32 v0, v206, v211, s78
	v_add_f32_e32 v88, v219, v220
	v_cmp_lt_i32_e32 vcc, 1, v0
	v_add_f32_e32 v90, v217, v218
	v_add_u32_e32 v141, 8, v141
	v_cndmask_b32_e32 v91, v193, v88, vcc
	v_pk_add_f32 v[88:89], v[156:157], v[158:159]
	v_cmp_lt_i32_e32 vcc, 3, v0
	v_max3_f32 v92, v208, v90, v91
	v_add_u32_e32 v211, -8, v211
	v_cndmask_b32_e32 v93, v193, v88, vcc
	v_cmp_lt_i32_e32 vcc, 2, v0
	s_nop 1
	v_cndmask_b32_e32 v94, v193, v89, vcc
	v_pk_add_f32 v[88:89], v[160:161], v[162:163]
	v_cmp_lt_i32_e32 vcc, 5, v0
	v_max3_f32 v92, v92, v94, v93
	s_nop 0
	v_cndmask_b32_e32 v95, v193, v88, vcc
	v_cmp_lt_i32_e32 vcc, 4, v0
	s_nop 1
	v_cndmask_b32_e32 v96, v193, v89, vcc
	v_pk_add_f32 v[88:89], v[164:165], v[166:167]
	v_cmp_lt_i32_e32 vcc, 7, v0
	v_max3_f32 v92, v92, v96, v95
	s_nop 0
	v_cndmask_b32_e32 v97, v193, v88, vcc
	v_cmp_lt_i32_e32 vcc, 6, v0
	s_nop 1
	v_cndmask_b32_e32 v89, v193, v89, vcc
	v_max3_f32 v0, v92, v89, v97
	v_sub_f32_e32 v92, v90, v0
	v_mul_f32_e32 v92, 0x3fb8aa3b, v92
	v_exp_f32_e32 v92, v92
	v_cmp_lt_f32_e32 vcc, s89, v90
	v_sub_f32_e32 v88, v208, v0
	v_mul_f32_e32 v88, 0x3fb8aa3b, v88
	v_cndmask_b32_e32 v90, 0, v92, vcc
	v_mov_b32_e32 v92, v90
	s_nop 0
	v_pk_mul_f32 v[86:87], v[86:87], v[90:91] op_sel_hi:[1,0]
	v_pk_mul_f32 v[84:85], v[84:85], v[90:91] op_sel_hi:[1,0]
	v_sub_f32_e32 v90, v91, v0
	v_mul_f32_e32 v90, 0x3fb8aa3b, v90
	v_exp_f32_e32 v88, v88
	v_exp_f32_e32 v90, v90
	v_cmp_lt_f32_e32 vcc, s89, v91
	v_mov_b32_e32 v208, v0
	v_fmac_f32_e32 v92, v209, v88
	v_pk_fma_f32 v[52:53], v[52:53], v[88:89], v[84:85] op_sel_hi:[1,0,1]
	v_pk_fma_f32 v[54:55], v[54:55], v[88:89], v[86:87] op_sel_hi:[1,0,1]
	v_cndmask_b32_e32 v84, 0, v90, vcc
	v_sub_f32_e32 v86, v94, v0
	v_add_f32_e32 v85, v84, v92
	v_mul_f32_e32 v86, 0x3fb8aa3b, v86
	v_exp_f32_e32 v86, v86
	s_nop 0
	v_pk_fma_f32 v[54:55], v[82:83], v[84:85], v[54:55] op_sel_hi:[1,0,1]
	v_sub_f32_e32 v82, v93, v0
	v_mul_f32_e32 v82, 0x3fb8aa3b, v82
	v_exp_f32_e32 v82, v82
	v_cmp_lt_f32_e32 vcc, s89, v94
	v_pk_fma_f32 v[52:53], v[80:81], v[84:85], v[52:53] op_sel_hi:[1,0,1]
	s_nop 0
	v_cndmask_b32_e32 v80, 0, v86, vcc
	v_add_f32_e32 v81, v80, v85
	v_cmp_lt_f32_e32 vcc, s89, v93
	s_nop 0
	v_pk_fma_f32 v[52:53], v[76:77], v[80:81], v[52:53] op_sel_hi:[1,0,1]
	v_pk_fma_f32 v[54:55], v[78:79], v[80:81], v[54:55] op_sel_hi:[1,0,1]
	v_cndmask_b32_e32 v76, 0, v82, vcc
	v_sub_f32_e32 v78, v96, v0
	v_add_f32_e32 v77, v76, v81
	v_mul_f32_e32 v78, 0x3fb8aa3b, v78
	v_exp_f32_e32 v78, v78
	s_nop 0
	v_pk_fma_f32 v[54:55], v[74:75], v[76:77], v[54:55] op_sel_hi:[1,0,1]
	v_sub_f32_e32 v74, v95, v0
	v_mul_f32_e32 v74, 0x3fb8aa3b, v74
	v_exp_f32_e32 v74, v74
	v_cmp_lt_f32_e32 vcc, s89, v96
	v_pk_fma_f32 v[52:53], v[72:73], v[76:77], v[52:53] op_sel_hi:[1,0,1]
	s_nop 0
	v_cndmask_b32_e32 v72, 0, v78, vcc
	v_add_f32_e32 v73, v72, v77
	v_cmp_lt_f32_e32 vcc, s89, v95
	s_nop 0
	v_pk_fma_f32 v[52:53], v[68:69], v[72:73], v[52:53] op_sel_hi:[1,0,1]
	v_pk_fma_f32 v[54:55], v[70:71], v[72:73], v[54:55] op_sel_hi:[1,0,1]
	v_cndmask_b32_e32 v68, 0, v74, vcc
	v_sub_f32_e32 v70, v89, v0
	v_add_f32_e32 v69, v68, v73
	v_mul_f32_e32 v70, 0x3fb8aa3b, v70
	v_exp_f32_e32 v70, v70
	s_nop 0
	v_pk_fma_f32 v[54:55], v[66:67], v[68:69], v[54:55] op_sel_hi:[1,0,1]
	v_sub_f32_e32 v66, v97, v0
	v_mul_f32_e32 v66, 0x3fb8aa3b, v66
	v_exp_f32_e32 v66, v66
	v_cmp_lt_f32_e32 vcc, s89, v89
	v_pk_fma_f32 v[52:53], v[64:65], v[68:69], v[52:53] op_sel_hi:[1,0,1]
	s_nop 0
	v_cndmask_b32_e32 v64, 0, v70, vcc
	v_add_f32_e32 v65, v64, v69
	v_cmp_lt_f32_e32 vcc, s89, v97
	s_nop 0
	v_pk_fma_f32 v[52:53], v[60:61], v[64:65], v[52:53] op_sel_hi:[1,0,1]
	v_pk_fma_f32 v[54:55], v[62:63], v[64:65], v[54:55] op_sel_hi:[1,0,1]
	v_cndmask_b32_e32 v60, 0, v66, vcc
	v_cmp_ge_u32_e32 vcc, v141, v206
	v_add_f32_e32 v209, v60, v65
	s_nop 0
	v_pk_fma_f32 v[54:55], v[58:59], v[60:61], v[54:55] op_sel_hi:[1,0,1]
	v_pk_fma_f32 v[52:53], v[56:57], v[60:61], v[52:53] op_sel_hi:[1,0,1]
	s_or_b64 s[26:27], vcc, s[26:27]
	s_andn2_b64 exec, exec, s[26:27]
	s_cbranch_execz .LBB0_467
	s_branch .LBB0_450
